# attention loop: weight-conversion slice keeps its lane-invariant address parts in spare registers (scalar-base LDS-DMA and stores), ~60 fewer VALU per iteration
# speedup vs baseline: 1.0096x; 1.0096x over previous
.LBB0_429:
	s_min_i32 s48, s25, 0x43
	v_lshlrev_b32_e32 v188, 3, v0
	v_mad_i64_i32 v[100:101], s[4:5], v98, s38, 0
	v_add_u32_e32 v193, 0, v190
	v_mad_u32_u24 v42, v218, s41, v193
	ds_read_b128 v[36:39], v42
	ds_read_b128 v[48:51], v42 offset:32
	ds_read_b128 v[52:55], v42 offset:64
	ds_read_b128 v[56:59], v42 offset:96
	ds_read_b128 v[60:63], v42 offset:4608
	ds_read_b128 v[102:105], v42 offset:4640
	ds_read_b128 v[106:109], v42 offset:4672
	s_waitcnt lgkmcnt(0)
	v_mfma_f32_32x32x16_bf16 v[0:15], v[36:39], v[132:135], 0
	ds_read_b128 v[110:113], v42 offset:4704
	v_add_co_u32_e32 v40, vcc, 0x2000, v34
	v_sub_u32_e32 v187, v193, v188
	s_nop 0
	v_addc_co_u32_e32 v41, vcc, 0, v35, vcc
	v_add_co_u32_e32 v34, vcc, 0x3000, v34
	v_mfma_f32_32x32x16_bf16 v[16:31], v[60:63], v[132:135], 0
	s_nop 0
	v_addc_co_u32_e32 v35, vcc, 0, v35, vcc
	global_load_dwordx4 v[84:87], v[40:41], off
	global_load_dwordx4 v[80:83], v[32:33], off offset:128
	v_add_co_u32_e32 v32, vcc, 0x44000, v32
	v_and_b32_e32 v41, 64, v181
	s_nop 0
	v_addc_co_u32_e32 v33, vcc, 0, v33, vcc
	v_mfma_f32_32x32x16_bf16 v[0:15], v[48:51], v[156:159], v[0:15]
	v_xor_b32_e32 v40, 32, v181
	v_add_u32_e32 v41, 64, v41
	v_cmp_lt_i32_e32 vcc, v40, v41
	global_load_dwordx4 v[92:95], v[34:35], off
	global_load_dwordx4 v[88:91], v[32:33], off offset:128
	v_cndmask_b32_e32 v40, v181, v40, vcc
	v_lshlrev_b32_e32 v191, 2, v40
	v_mul_u32_u24_e32 v215, 0x90, v218
	v_mfma_f32_32x32x16_bf16 v[16:31], v[102:105], v[156:159], v[16:31]
	s_mov_b32 s50, 2
	s_movk_i32 s52, 0x4000
	v_mfma_f32_32x32x16_bf16 v[0:15], v[52:55], v[152:155], v[0:15]
	v_mfma_f32_32x32x16_bf16 v[16:31], v[106:109], v[152:155], v[16:31]
	s_waitcnt lgkmcnt(0)
	v_mfma_f32_32x32x16_bf16 v[16:31], v[110:113], v[148:151], v[16:31]
	v_mfma_f32_32x32x16_bf16 v[0:15], v[56:59], v[148:151], v[0:15]
	s_nop 10
	v_max_f32_e32 v40, v16, v16
	v_max_f32_e32 v41, v0, v0
	v_max_f32_e32 v40, v41, v40
	v_max3_f32 v40, v40, v1, v17
	v_max3_f32 v40, v40, v2, v18
	v_max3_f32 v40, v40, v3, v19
	v_max3_f32 v40, v40, v4, v20
	v_max3_f32 v40, v40, v5, v21
	v_max3_f32 v40, v40, v6, v22
	v_max3_f32 v40, v40, v7, v23
	v_max3_f32 v40, v40, v8, v24
	v_max3_f32 v40, v40, v9, v25
	v_max3_f32 v40, v40, v10, v26
	v_max3_f32 v40, v40, v11, v27
	v_max3_f32 v40, v40, v12, v28
	v_max3_f32 v40, v40, v13, v29
	v_max3_f32 v40, v40, v14, v30
	v_max3_f32 v40, v40, v15, v31
	ds_bpermute_b32 v41, v191, v40
	s_waitcnt lgkmcnt(0)
	v_max3_f32 v64, v40, v41, s43
	v_cmp_lt_f32_e32 vcc, s43, v64
	s_cmp_eq_u64 vcc, 0
	v_sub_f32_e32 v32, 0xf149f2ca, v64
	s_cselect_b64 vcc, -1, 0
	v_exp_f32_e32 v220, v32
	s_waitcnt vmcnt(0)
	v_mfma_f32_32x32x16_bf16 v[32:47], v[36:39], v[172:175], 0
	v_cndmask_b32_e32 v216, v64, v214, vcc
	v_sub_f32_e32 v1, v1, v216
	v_sub_f32_e32 v0, v0, v216
	v_exp_f32_e32 v202, v0
	v_exp_f32_e32 v200, v1
	v_sub_f32_e32 v16, v16, v216
	v_exp_f32_e32 v136, v16
	v_mfma_f32_32x32x16_bf16 v[64:79], v[60:63], v[172:175], 0
	v_sub_f32_e32 v7, v7, v216
	v_sub_f32_e32 v6, v6, v216
	v_sub_f32_e32 v5, v5, v216
	v_sub_f32_e32 v4, v4, v216
	v_sub_f32_e32 v3, v3, v216
	v_sub_f32_e32 v2, v2, v216
	v_exp_f32_e32 v210, v2
	v_mfma_f32_32x32x16_bf16 v[32:47], v[48:51], v[168:171], v[32:47]
	v_exp_f32_e32 v208, v3
	v_exp_f32_e32 v206, v4
	v_exp_f32_e32 v204, v5
	v_exp_f32_e32 v198, v6
	v_exp_f32_e32 v196, v7
	v_sub_f32_e32 v15, v15, v216
	v_sub_f32_e32 v14, v14, v216
	v_mfma_f32_32x32x16_bf16 v[64:79], v[102:105], v[168:171], v[64:79]
	v_sub_f32_e32 v13, v13, v216
	v_sub_f32_e32 v12, v12, v216
	v_sub_f32_e32 v11, v11, v216
	v_sub_f32_e32 v10, v10, v216
	v_sub_f32_e32 v9, v9, v216
	v_sub_f32_e32 v8, v8, v216
	v_sub_f32_e32 v31, v31, v216
	v_mfma_f32_32x32x16_bf16 v[32:47], v[52:55], v[164:167], v[32:47]
	v_sub_f32_e32 v30, v30, v216
	v_sub_f32_e32 v29, v29, v216
	v_sub_f32_e32 v28, v28, v216
	v_sub_f32_e32 v27, v27, v216
	v_sub_f32_e32 v26, v26, v216
	v_sub_f32_e32 v25, v25, v216
	v_sub_f32_e32 v24, v24, v216
	v_mfma_f32_32x32x16_bf16 v[64:79], v[106:109], v[164:167], v[64:79]
	v_sub_f32_e32 v23, v23, v216
	v_sub_f32_e32 v22, v22, v216
	v_sub_f32_e32 v21, v21, v216
	v_sub_f32_e32 v20, v20, v216
	v_sub_f32_e32 v19, v19, v216
	v_sub_f32_e32 v18, v18, v216
	v_sub_f32_e32 v17, v17, v216
	v_mfma_f32_32x32x16_bf16 v[32:47], v[56:59], v[160:163], v[32:47]
	v_exp_f32_e32 v194, v8
	v_exp_f32_e32 v178, v9
	v_exp_f32_e32 v176, v10
	v_exp_f32_e32 v146, v11
	v_exp_f32_e32 v144, v12
	v_exp_f32_e32 v142, v13
	v_exp_f32_e32 v140, v14
	v_mfma_f32_32x32x16_bf16 v[64:79], v[110:113], v[160:163], v[64:79]
	s_nop 3
	v_max_f32_e32 v1, v32, v32
	v_exp_f32_e32 v138, v15
	v_exp_f32_e32 v130, v17
	v_exp_f32_e32 v128, v18
	v_exp_f32_e32 v116, v19
	v_exp_f32_e32 v114, v20
	v_exp_f32_e32 v112, v21
	s_nop 0
	v_max_f32_e32 v0, v64, v64
	v_max_f32_e32 v0, v1, v0
	v_max3_f32 v0, v0, v33, v65
	v_max3_f32 v0, v0, v34, v66
	v_max3_f32 v0, v0, v35, v67
	v_max3_f32 v0, v0, v36, v68
	v_max3_f32 v0, v0, v37, v69
	v_max3_f32 v0, v0, v38, v70
	v_max3_f32 v0, v0, v39, v71
	v_max3_f32 v0, v0, v40, v72
	v_max3_f32 v0, v0, v41, v73
	v_max3_f32 v0, v0, v42, v74
	v_max3_f32 v0, v0, v43, v75
	v_max3_f32 v0, v0, v44, v76
	v_max3_f32 v0, v0, v45, v77
	v_max3_f32 v0, v0, v46, v78
	v_max3_f32 v0, v0, v47, v79
	ds_bpermute_b32 v1, v191, v0
	v_exp_f32_e32 v110, v22
	v_exp_f32_e32 v108, v23
	v_exp_f32_e32 v106, v24
	v_exp_f32_e32 v104, v25
	s_waitcnt lgkmcnt(0)
	v_max3_f32 v48, v0, v1, s43
	v_sub_f32_e32 v0, 0xf149f2ca, v48
	v_exp_f32_e32 v221, v0
	v_cmp_lt_f32_e64 s[4:5], s43, v48
	s_cmp_eq_u64 s[4:5], 0
	v_exp_f32_e32 v102, v26
	v_pk_mul_f32 v[0:1], v[220:221], 0 op_sel_hi:[1,0]
	v_exp_f32_e32 v124, v27
	v_cndmask_b32_e64 v16, v0, 0, vcc
	s_cselect_b64 vcc, -1, 0
	v_cndmask_b32_e32 v217, v48, v214, vcc
	v_sub_f32_e32 v32, v32, v217
	v_exp_f32_e32 v203, v32
	v_mad_u32_u24 v32, v218, s44, v187
	v_add_u32_e32 v233, 0x2000, v32
	v_sub_f32_e32 v121, v77, v217
	v_sub_f32_e32 v123, v76, v217
	v_sub_f32_e32 v125, v75, v217
	v_sub_f32_e32 v219, v74, v217
	ds_read2_b64 v[74:77], v233 offset0:128 offset1:130
	v_sub_f32_e32 v39, v39, v217
	v_sub_f32_e32 v38, v38, v217
	v_sub_f32_e32 v37, v37, v217
	v_sub_f32_e32 v36, v36, v217
	v_sub_f32_e32 v35, v35, v217
	v_sub_f32_e32 v34, v34, v217
	v_sub_f32_e32 v33, v33, v217
	v_exp_f32_e32 v201, v33
	v_exp_f32_e32 v211, v34
	v_exp_f32_e32 v209, v35
	v_exp_f32_e32 v207, v36
	v_exp_f32_e32 v205, v37
	v_exp_f32_e32 v199, v38
	v_exp_f32_e32 v197, v39
	v_cndmask_b32_e64 v0, v1, 0, vcc
	v_exp_f32_e32 v122, v28
	v_exp_f32_e32 v120, v29
	v_exp_f32_e32 v118, v30
	v_exp_f32_e32 v126, v31
	v_mov_b32_e32 v17, v16
	v_mov_b32_e32 v18, v16
	v_mov_b32_e32 v19, v16
	v_mov_b32_e32 v20, v16
	v_mov_b32_e32 v21, v16
	v_mov_b32_e32 v22, v16
	v_mov_b32_e32 v23, v16
	v_mov_b32_e32 v24, v16
	v_mov_b32_e32 v25, v16
	v_mov_b32_e32 v26, v16
	v_mov_b32_e32 v27, v16
	v_mov_b32_e32 v28, v16
	v_mov_b32_e32 v29, v16
	v_mov_b32_e32 v30, v16
	v_mov_b32_e32 v31, v16
	v_mov_b32_e32 v1, v0
	v_mov_b32_e32 v2, v0
	v_mov_b32_e32 v3, v0
	v_mov_b32_e32 v4, v0
	v_mov_b32_e32 v5, v0
	v_mov_b32_e32 v6, v0
	v_mov_b32_e32 v7, v0
	v_mov_b32_e32 v8, v0
	v_mov_b32_e32 v9, v0
	v_mov_b32_e32 v10, v0
	v_mov_b32_e32 v11, v0
	v_mov_b32_e32 v12, v0
	v_mov_b32_e32 v13, v0
	v_mov_b32_e32 v14, v0
	v_mov_b32_e32 v15, v0
	v_cvt_pk_bf16_f32 v220, v202, v200
	v_cvt_pk_bf16_f32 v221, v210, v208
	v_cvt_pk_bf16_f32 v222, v206, v204
	v_cvt_pk_bf16_f32 v223, v198, v196
	v_cvt_pk_bf16_f32 v224, v203, v201
	v_cvt_pk_bf16_f32 v225, v211, v209
	v_cvt_pk_bf16_f32 v226, v207, v205
	v_cvt_pk_bf16_f32 v227, v199, v197
	v_sub_f32_e32 v238, v69, v217
	v_sub_f32_e32 v239, v68, v217
	v_sub_f32_e32 v240, v67, v217
	v_sub_f32_e32 v129, v66, v217
	ds_read2_b64 v[66:69], v233 offset0:132 offset1:134
	v_sub_f32_e32 v103, v47, v217
	v_sub_f32_e32 v105, v46, v217
	v_sub_f32_e32 v107, v45, v217
	v_sub_f32_e32 v109, v44, v217
	v_sub_f32_e32 v111, v43, v217
	v_sub_f32_e32 v113, v42, v217
	v_sub_f32_e32 v115, v41, v217
	v_sub_f32_e32 v117, v40, v217
	s_waitcnt lgkmcnt(1)
	v_mfma_f32_32x32x16_bf16 v[48:63], v[74:77], v[220:223], v[16:31]
	v_add_u32_e32 v234, 0x3000, v32
	v_exp_f32_e32 v195, v117
	v_exp_f32_e32 v179, v115
	v_exp_f32_e32 v177, v113
	v_exp_f32_e32 v147, v111
	v_exp_f32_e32 v145, v109
	v_exp_f32_e32 v143, v107
	v_mfma_f32_32x32x16_bf16 v[32:47], v[74:77], v[224:227], v[0:15]
	v_exp_f32_e32 v141, v105
	v_exp_f32_e32 v139, v103
	ds_read2_b64 v[228:231], v234 offset0:160 offset1:162
	v_sub_f32_e32 v127, v79, v217
	v_sub_f32_e32 v119, v78, v217
	v_sub_f32_e32 v232, v73, v217
	v_sub_f32_e32 v235, v72, v217
	v_sub_f32_e32 v236, v71, v217
	v_sub_f32_e32 v237, v70, v217
	v_mov_b32_e32 v78, v16
	v_mov_b32_e32 v79, v0
	v_cvt_pk_bf16_f32 v70, v194, v178
	v_cvt_pk_bf16_f32 v71, v176, v146
	v_cvt_pk_bf16_f32 v72, v144, v142
	v_cvt_pk_bf16_f32 v73, v140, v138
	v_cvt_pk_bf16_f32 v74, v195, v179
	v_cvt_pk_bf16_f32 v75, v177, v147
	v_cvt_pk_bf16_f32 v76, v145, v143
	v_cvt_pk_bf16_f32 v77, v141, v139
	v_sub_f32_e32 v131, v65, v217
	s_waitcnt lgkmcnt(1)
	v_mfma_f32_32x32x16_bf16 v[48:63], v[66:69], v[70:73], v[48:63]
	v_exp_f32_e32 v131, v131
	v_exp_f32_e32 v129, v129
	v_exp_f32_e32 v117, v240
	v_exp_f32_e32 v115, v239
	v_exp_f32_e32 v113, v238
	v_exp_f32_e32 v111, v237
	v_exp_f32_e32 v109, v236
	v_mfma_f32_32x32x16_bf16 v[32:47], v[66:69], v[74:77], v[32:47]
	v_sub_f32_e32 v66, v64, v217
	v_add_f32_e64 v64, v78, v202
	v_add_f32_e64 v65, v79, v203
	v_exp_f32_e32 v137, v66
	v_pk_add_f32 v[64:65], v[200:201], v[64:65]
	v_cvt_pk_bf16_f32 v68, v136, v130
	v_pk_add_f32 v[64:65], v[210:211], v[64:65]
	v_cvt_pk_bf16_f32 v69, v128, v116
	v_pk_add_f32 v[64:65], v[208:209], v[64:65]
	s_waitcnt lgkmcnt(0)
	v_mfma_f32_32x32x16_bf16 v[16:31], v[228:231], v[220:223], v[16:31]
	v_add_f32_e64 v64, v206, v64
	v_add_f32_e64 v65, v207, v65
	ds_read2_b64 v[220:223], v234 offset0:164 offset1:166
	v_add_f32_e64 v64, v204, v64
	v_add_f32_e64 v65, v205, v65
	v_exp_f32_e32 v107, v235
	v_pk_add_f32 v[64:65], v[198:199], v[64:65]
	v_exp_f32_e32 v105, v232
	v_pk_add_f32 v[64:65], v[196:197], v[64:65]
	v_mfma_f32_32x32x16_bf16 v[0:15], v[228:231], v[224:227], v[0:15]
	v_add_f32_e64 v194, v194, v64
	v_add_f32_e64 v195, v195, v65
	ds_read2_b64 v[64:67], v233 offset0:136 offset1:138
	v_exp_f32_e32 v103, v219
	v_exp_f32_e32 v125, v125
	v_exp_f32_e32 v123, v123
	v_exp_f32_e32 v121, v121
	v_exp_f32_e32 v119, v119
	s_waitcnt lgkmcnt(1)
	v_mfma_f32_32x32x16_bf16 v[16:31], v[220:223], v[70:73], v[16:31]
	v_cvt_pk_bf16_f32 v70, v114, v112
	v_cvt_pk_bf16_f32 v71, v110, v108
	v_cvt_pk_bf16_f32 v72, v137, v131
	v_cvt_pk_bf16_f32 v73, v129, v117
	v_exp_f32_e32 v127, v127
	v_mad_u64_u32 v[196:197], s[4:5], v98, s44, v[182:183]
	v_mfma_f32_32x32x16_bf16 v[0:15], v[220:223], v[74:77], v[0:15]
	v_cvt_pk_bf16_f32 v74, v115, v113
	v_cvt_pk_bf16_f32 v75, v111, v109
	ds_read2_b64 v[76:79], v234 offset0:168 offset1:170
	s_add_i32 s0, s31, 1
	v_readlane_b32 s4, v255, 0
	s_mul_i32 s51, s33, s0
	s_mov_b32 s53, s4
	s_waitcnt lgkmcnt(1)
	v_mfma_f32_32x32x16_bf16 v[48:63], v[64:67], v[68:71], v[48:63]
	v_readlane_b32 s5, v255, 1
	v_mfma_f32_32x32x16_bf16 v[32:47], v[64:67], v[72:75], v[32:47]
	v_add_f32_e64 v64, v178, v194
	v_add_f32_e64 v65, v179, v195
	v_add_f32_e64 v64, v176, v64
	v_add_f32_e64 v65, v177, v65
	v_add_f32_e64 v64, v146, v64
	v_add_f32_e64 v65, v147, v65
	v_pk_add_f32 v[64:65], v[144:145], v[64:65]
	s_waitcnt lgkmcnt(0)
	v_mfma_f32_32x32x16_bf16 v[16:31], v[76:79], v[68:71], v[16:31]
	v_add_f32_e64 v64, v142, v64
	v_add_f32_e64 v65, v143, v65
	v_cvt_pk_bf16_f32 v68, v106, v104
	v_add_f32_e64 v64, v140, v64
	v_add_f32_e64 v65, v141, v65
	v_cvt_pk_bf16_f32 v69, v102, v124
	v_pk_add_f32 v[64:65], v[138:139], v[64:65]
	v_cvt_pk_bf16_f32 v70, v122, v120
	v_pk_add_f32 v[64:65], v[136:137], v[64:65]
	v_mfma_f32_32x32x16_bf16 v[0:15], v[76:79], v[72:75], v[0:15]
	v_add_f32_e64 v64, v130, v64
	v_add_f32_e64 v65, v131, v65
	v_cvt_pk_bf16_f32 v71, v118, v126
	v_add_f32_e64 v128, v128, v64
	v_add_f32_e64 v129, v129, v65
	ds_read2_b64 v[64:67], v233 offset0:140 offset1:142
	v_cvt_pk_bf16_f32 v72, v107, v105
	v_cvt_pk_bf16_f32 v73, v103, v125
	v_cvt_pk_bf16_f32 v74, v123, v121
	v_cvt_pk_bf16_f32 v75, v119, v127
	s_waitcnt lgkmcnt(0)
	v_mfma_f32_32x32x16_bf16 v[48:63], v[64:67], v[68:71], v[48:63]
	ds_read2_b64 v[76:79], v234 offset0:172 offset1:174
	v_mfma_f32_32x32x16_bf16 v[32:47], v[64:67], v[72:75], v[32:47]
	v_add_f32_e64 v64, v116, v128
	v_add_f32_e64 v65, v117, v129
	v_add_f32_e64 v64, v114, v64
	v_add_f32_e64 v65, v115, v65
	v_add_f32_e64 v64, v112, v64
	v_add_f32_e64 v65, v113, v65
	v_pk_add_f32 v[64:65], v[110:111], v[64:65]
	s_waitcnt lgkmcnt(0)
	v_mfma_f32_32x32x16_bf16 v[16:31], v[76:79], v[68:71], v[16:31]
	v_add_f32_e64 v64, v108, v64
	v_add_f32_e64 v65, v109, v65
	v_add_f32_e64 v64, v106, v64
	v_add_f32_e64 v65, v107, v65
	v_add_f32_e64 v64, v104, v64
	v_add_f32_e64 v65, v105, v65
	v_pk_add_f32 v[64:65], v[102:103], v[64:65]
	v_mfma_f32_32x32x16_bf16 v[0:15], v[76:79], v[72:75], v[0:15]
	v_add_f32_e64 v64, v124, v64
	v_add_f32_e64 v65, v125, v65
	v_add_f32_e64 v64, v122, v64
	v_add_f32_e64 v65, v123, v65
	v_add_f32_e64 v64, v120, v64
	v_add_f32_e64 v65, v121, v65
	v_pk_add_f32 v[64:65], v[118:119], v[64:65]
	s_nop 0
	v_pk_add_f32 v[194:195], v[126:127], v[64:65]
	v_add_u32_e32 v64, 0, v196
	v_add_u32_e32 v66, 0x6a00, v64
	v_add_u32_e32 v64, 0x7b00, v64
	ds_write_b128 v99, v[84:87] offset:17920
	ds_write_b128 v99, v[92:95] offset:22528
	ds_write2_b64 v66, v[80:81], v[82:83] offset1:1
	ds_write2_b64 v64, v[88:89], v[90:91] offset1:1
	v_and_b32_e32 v64, 7, v189
	v_lshlrev_b32_e32 v182, 4, v64
	s_waitcnt vmcnt(0)
	v_lshl_add_u64 v[66:67], v[96:97], 0, v[182:183]
	v_lshl_add_u64 v[198:199], s[94:95], 0, v[66:67]
	v_lshl_add_u64 v[66:67], v[100:101], 0, v[182:183]
	v_mul_u32_u24_e32 v65, 0x88, v218
	v_lshl_add_u64 v[200:201], s[94:95], 0, v[66:67]
	s_waitcnt lgkmcnt(0)
	s_barrier
	v_lshrrev_b32_e32 v241, 4, v189
	v_and_b32_e32 v242, 15, v189
	v_bfe_u32 v245, v189, 7, 1
	v_xor_b32_e32 v242, v242, v245
	v_lshlrev_b32_e32 v242, 4, v242
	v_lshrrev_b32_e32 v245, 6, v189
	v_lshlrev_b32_e32 v245, 10, v245
	v_and_b32_e32 v244, 7, v189
	v_readfirstlane_b32 s98, v245
	v_lshrrev_b32_e32 v243, 5, v189
	v_xor_b32_e32 v243, v243, v244
	v_and_b32_e32 v243, 15, v243
	v_lshlrev_b32_e32 v243, 4, v243
	v_bfe_u32 v245, v189, 3, 2
	v_lshl_add_u32 v243, v245, 2, v243
	v_lshl_add_u32 v243, v244, 11, v243
	v_lshrrev_b32_e32 v245, 3, v189
	v_lshlrev_b32_e32 v245, 11, v245
	v_lshl_add_u32 v244, v244, 4, v245

.LBB0_440:
	s_mulk_i32 s56, 0xfa00
	s_add_i32 s59, s54, s56
	s_lshl_b64 s[56:57], s[0:1], 2
	s_add_u32 s4, s4, s56
	s_addc_u32 s5, s5, s57
	s_mul_i32 s56, s58, s26
	s_lshl_b32 s56, s56, 2
	s_add_u32 s4, s4, s56
	s_addc_u32 s5, s5, 0
	s_lshl_b32 s57, s26, 2
	v_mul_u32_u24_e32 v66, s57, v241
	s_lshl_b32 s56, s26, 6
	s_add_i32 s0, s59, s98
	s_add_i32 s0, s0, 0x9000
	s_mov_b32 m0, s0
	v_add_u32_e32 v66, v66, v242
	global_load_lds_dwordx4 v66, s[4:5] nt
	s_add_u32 s4, s4, s56
	s_addc_u32 s5, s5, 0
	s_add_i32 s0, s0, 0x1000
	s_mov_b32 m0, s0
	v_xor_b32_e32 v67, 0x20, v66
	global_load_lds_dwordx4 v67, s[4:5] nt
	s_add_u32 s4, s4, s56
	s_addc_u32 s5, s5, 0
	s_add_i32 s0, s0, 0x1000
	s_mov_b32 m0, s0
	v_xor_b32_e32 v68, 0x40, v66
	global_load_lds_dwordx4 v68, s[4:5] nt
	s_add_u32 s4, s4, s56
	s_addc_u32 s5, s5, 0
	s_add_i32 s0, s0, 0x1000
	s_mov_b32 m0, s0
	v_xor_b32_e32 v69, 0x60, v66
	global_load_lds_dwordx4 v69, s[4:5] nt

.LBB0_451:
	s_andn2_b32 s26, 0x4000, s52
	s_add_i32 s56, s26, 0
	v_add_u32_e32 v72, s56, v243
	ds_read2st64_b32 v[66:67], v72 offset0:144 offset1:145
	ds_read2st64_b32 v[68:69], v72 offset0:146 offset1:147
	ds_read2st64_b32 v[70:71], v72 offset0:148 offset1:149
	v_xor_b32_e32 v64, 0x80, v72
	ds_read2st64_b32 v[72:73], v72 offset0:150 offset1:151
	ds_read2st64_b32 v[74:75], v64 offset0:144 offset1:145
	ds_read2st64_b32 v[76:77], v64 offset0:146 offset1:147
	ds_read2st64_b32 v[78:79], v64 offset0:148 offset1:149
	ds_read2st64_b32 v[80:81], v64 offset0:150 offset1:151
	s_lshl_b64 s[26:27], s[0:1], 1
	s_add_u32 s4, s4, s26
	s_addc_u32 s5, s5, s27
	s_lshl_b32 s26, s55, 11
	s_add_u32 s4, s4, s26
	s_addc_u32 s5, s5, 0
	s_waitcnt lgkmcnt(4)
	v_cvt_pk_bf16_f32 v66, v66, v67
	v_cvt_pk_bf16_f32 v67, v68, v69
	v_cvt_pk_bf16_f32 v68, v70, v71
	v_cvt_pk_bf16_f32 v69, v72, v73
	global_store_dwordx4 v244, v[66:69], s[4:5] sc1 nt
	s_add_u32 s4, s4, 0x10000
	s_addc_u32 s5, s5, 0
	s_waitcnt lgkmcnt(0)
	v_cvt_pk_bf16_f32 v74, v74, v75
	v_cvt_pk_bf16_f32 v75, v76, v77
	v_cvt_pk_bf16_f32 v76, v78, v79
	v_cvt_pk_bf16_f32 v77, v80, v81
	global_store_dwordx4 v244, v[74:77], s[4:5] sc1 nt

	.amdhsa_kernel _Z14fwd_megakernel6Params
		.amdhsa_group_segment_fixed_size 8176
		.amdhsa_private_segment_fixed_size 0
		.amdhsa_kernarg_size 464
		.amdhsa_user_sgpr_count 2
		.amdhsa_user_sgpr_dispatch_ptr 0
		.amdhsa_user_sgpr_queue_ptr 0
		.amdhsa_user_sgpr_kernarg_segment_ptr 1
		.amdhsa_user_sgpr_dispatch_id 0
		.amdhsa_user_sgpr_kernarg_preload_length 0
		.amdhsa_user_sgpr_kernarg_preload_offset 0
		.amdhsa_user_sgpr_private_segment_size 0
		.amdhsa_uses_dynamic_stack 0
		.amdhsa_enable_private_segment 0
		.amdhsa_system_sgpr_workgroup_id_x 1
		.amdhsa_system_sgpr_workgroup_id_y 0
		.amdhsa_system_sgpr_workgroup_id_z 0
		.amdhsa_system_sgpr_workgroup_info 0
		.amdhsa_system_vgpr_workitem_id 2
		.amdhsa_next_free_vgpr 256
		.amdhsa_next_free_sgpr 99
		.amdhsa_accum_offset 256
		.amdhsa_reserve_vcc 1
		.amdhsa_float_round_mode_32 0
		.amdhsa_float_round_mode_16_64 0
		.amdhsa_float_denorm_mode_32 3
		.amdhsa_float_denorm_mode_16_64 3
		.amdhsa_dx10_clamp 1
		.amdhsa_ieee_mode 1
		.amdhsa_fp16_overflow 0
		.amdhsa_tg_split 0
		.amdhsa_exception_fp_ieee_invalid_op 0
		.amdhsa_exception_fp_denorm_src 0
		.amdhsa_exception_fp_ieee_div_zero 0
		.amdhsa_exception_fp_ieee_overflow 0
		.amdhsa_exception_fp_ieee_underflow 0
		.amdhsa_exception_fp_ieee_inexact 0
		.amdhsa_exception_int_div_zero 0
	.end_amdhsa_kernel

amdhsa.kernels:
  - .agpr_count:     0
    .args:
      - .offset:         0
        .size:           208
        .value_kind:     by_value
      - .offset:         208
        .size:           4
        .value_kind:     hidden_block_count_x
      - .offset:         212
        .size:           4
        .value_kind:     hidden_block_count_y
      - .offset:         216
        .size:           4
        .value_kind:     hidden_block_count_z
      - .offset:         220
        .size:           2
        .value_kind:     hidden_group_size_x
      - .offset:         222
        .size:           2
        .value_kind:     hidden_group_size_y
      - .offset:         224
        .size:           2
        .value_kind:     hidden_group_size_z
      - .offset:         226
        .size:           2
        .value_kind:     hidden_remainder_x
      - .offset:         228
        .size:           2
        .value_kind:     hidden_remainder_y
      - .offset:         230
        .size:           2
        .value_kind:     hidden_remainder_z
      - .offset:         248
        .size:           8
        .value_kind:     hidden_global_offset_x
      - .offset:         256
        .size:           8
        .value_kind:     hidden_global_offset_y
      - .offset:         264
        .size:           8
        .value_kind:     hidden_global_offset_z
      - .offset:         272
        .size:           2
        .value_kind:     hidden_grid_dims
      - .offset:         296
        .size:           8
        .value_kind:     hidden_multigrid_sync_arg
      - .offset:         328
        .size:           4
        .value_kind:     hidden_dynamic_lds_size
    .group_segment_fixed_size: 8176
    .kernarg_segment_align: 8
    .kernarg_segment_size: 464
    .language:       OpenCL C
    .language_version:
      - 2
      - 0
    .max_flat_workgroup_size: 256
    .name:           _Z14fwd_megakernel6Params
    .private_segment_fixed_size: 0
    .sgpr_count:     105
    .sgpr_spill_count: 48
    .symbol:         _Z14fwd_megakernel6Params.kd
    .uniform_work_group_size: 1
    .uses_dynamic_stack: false
    .vgpr_count:     256
    .vgpr_spill_count: 0
    .wavefront_size: 64
